# hoist_stats_loads_p7_epilogue
# speedup vs baseline: 1.0029x; 1.0029x over previous
; __device__ __forceinline__ unsigned pk2(float lo, float hi) { f32x2v v = {lo, hi}; b16x2v b = __builtin_convertvector(v, b16x2v); return __builtin_bit_cast(unsigned, b); }
;     __device__ __forceinline__ bf16_t* O() const { return (bf16_t*)(ws + WS_O); }
;     __device__ __forceinline__ void operator()(const f32x4 (&acc)[2][2][4][2], const Unit& u, int wr, int wc, int fr, int fq) const {
;         const int colb = u.pn * 256 + 32 * wc + 8 * fq;
;         f32x4 c1v[2][2], c2v[2][2];
; #pragma unroll
;         for (int bj = 0; bj < 2; ++bj)
; #pragma unroll
;             for (int n = 0; n < 2; ++n) { const int col = colb + 128 * bj + 4 * n; c1v[bj][n] = *(const f32x4*)(c1 + col); c2v[bj][n] = *(const f32x4*)(c2 + col);
;                 if (HAS_BIAS) c2v[bj][n] = c2v[bj][n] + *(const f32x4*)(bias + col); }
; #pragma unroll
;         for (int ai = 0; ai < 2; ++ai)
; #pragma unroll
;             for (int m = 0; m < 4; ++m) {
;                 const int row = u.pm * 256 + ai * 128 + wr * 64 + m * 16 + fr;
;                 const f32x2v s2 = *(const f32x2v*)(stp + 2 * row); const float mu = s2.x * (1.0f / DM); const float rs = rsqrtf(fmaxf(s2.y * (1.0f / DM) - mu * mu, 0.f) + LN_EPS);
; #pragma unroll
;                 for (int bj = 0; bj < 2; ++bj) {
;                     f32x4 v0 = (acc[ai][bj][m][0] - c1v[bj][0] * mu) * rs + c2v[bj][0], v1 = (acc[ai][bj][m][1] - c1v[bj][1] * mu) * rs + c2v[bj][1];
;                     if (ACT == 1) {
; #pragma unroll
;                         for (int e = 0; e < 4; ++e) { const float a = fmaxf(v0[e], 0.f), c = fmaxf(v1[e], 0.f); v0[e] = a * a; v1[e] = c * c; }
;                     }
;                     v0 = v0 * scale; v1 = v1 * scale;
;                     u32x4 w; w.x = pk2(v0[0], v0[1]); w.y = pk2(v0[2], v0[3]); w.z = pk2(v1[0], v1[1]); w.w = pk2(v1[2], v1[3]);
;                     *(u32x4*)(O + (size_t)row * ldc + colb + 128 * bj) = w;
;                 }
;             }
;     }
.LBB0_1123:
	v_lshl_or_b32 v160, s1, 8, v187
	v_lshl_add_u32 v178, s0, 8, v185
	v_ashrrev_i32_e32 v161, 31, v160
	v_lshlrev_b32_e32 v92, 1, v178
	v_lshlrev_b64 v[88:89], 2, v[160:161]
	v_ashrrev_i32_e32 v93, 31, v92
	v_lshl_add_u64 v[84:85], s[8:9], 0, v[88:89]
	v_lshl_add_u64 v[90:91], s[10:11], 0, v[88:89]
	v_lshl_add_u64 v[88:89], s[46:47], 0, v[88:89]
	v_lshl_add_u64 v[92:93], v[92:93], 2, s[6:7]
	global_load_dwordx4 v[80:83], v[84:85], off offset:16
	s_nop 0
	global_load_dwordx4 v[84:87], v[84:85], off
	s_nop 0
	global_load_dwordx4 v[166:169], v[90:91], off offset:16
	global_load_dwordx4 v[162:165], v[90:91], off
	global_load_dwordx4 v[174:177], v[88:89], off offset:16
	global_load_dwordx4 v[194:197], v[88:89], off
	global_load_dwordx2 v[170:171], v[92:93], off
	global_load_dwordx2 v[216:217], v[92:93], off offset:128
	global_load_dwordx2 v[218:219], v[92:93], off offset:256
	global_load_dwordx2 v[220:221], v[92:93], off offset:384
	global_load_dwordx2 v[222:223], v[92:93], off offset:1024
	global_load_dwordx2 v[224:225], v[92:93], off offset:1152
	global_load_dwordx2 v[226:227], v[92:93], off offset:1280
	global_load_dwordx2 v[228:229], v[92:93], off offset:1408
	v_or_b32_e32 v90, 0x80, v160
	v_ashrrev_i32_e32 v91, 31, v90
	v_lshlrev_b64 v[90:91], 2, v[90:91]
	v_lshl_add_u64 v[92:93], s[10:11], 0, v[90:91]
	global_load_dwordx4 v[198:201], v[92:93], off
	global_load_dwordx4 v[202:205], v[88:89], off offset:512
	global_load_dwordx4 v[206:209], v[88:89], off offset:528
	global_load_dwordx4 v[210:213], v[92:93], off offset:16
	v_lshl_add_u64 v[88:89], s[8:9], 0, v[90:91]
	global_load_dwordx4 v[92:95], v[88:89], off
	v_or_b32_e32 v88, 0x84, v160
	v_ashrrev_i32_e32 v89, 31, v88
	v_lshl_add_u64 v[88:89], v[88:89], 2, s[8:9]
	global_load_dwordx4 v[88:91], v[88:89], off
	v_ashrrev_i32_e32 v179, 31, v178
	v_lshlrev_b64 v[214:215], 13, v[178:179]
	v_lshlrev_b64 v[172:173], 1, v[160:161]
	v_lshl_add_u64 v[160:161], s[4:5], 0, v[214:215]
	v_lshl_add_u64 v[214:215], v[160:161], 0, v[172:173]
	s_waitcnt vmcnt(0)
	v_pk_add_f32 v[166:167], v[166:167], v[174:175]
	v_pk_add_f32 v[162:163], v[162:163], v[194:195]
	v_pk_mul_f32 v[194:195], v[170:171], s[22:23] op_sel_hi:[1,0]
	v_pk_add_f32 v[160:161], v[164:165], v[196:197]
	v_fma_f32 v179, -v194, v194, v195
	v_max_f32_e32 v179, 0, v179
	v_add_f32_e32 v179, 0x3727c5ac, v179
	v_mul_f32_e32 v191, 0x4b800000, v179
	v_cmp_gt_f32_e32 vcc, s63, v179
	v_pk_add_f32 v[164:165], v[168:169], v[176:177]
	v_xor_b32_e32 v177, 0x80000000, v87
	v_cndmask_b32_e32 v179, v179, v191, vcc
	v_rsq_f32_e32 v179, v179
	v_xor_b32_e32 v176, 0x80000000, v86
	v_xor_b32_e32 v175, 0x80000000, v83
	v_xor_b32_e32 v174, 0x80000000, v82
	v_xor_b32_e32 v95, 0x80000000, v95
	v_xor_b32_e32 v94, 0x80000000, v94
	v_xor_b32_e32 v91, 0x80000000, v91
	v_xor_b32_e32 v90, 0x80000000, v90
	v_mul_f32_e32 v191, 0x45800000, v179
	v_pk_fma_f32 v[140:141], v[84:85], v[194:195], v[140:141] op_sel_hi:[1,0,1] neg_lo:[1,0,0] neg_hi:[1,0,0]
	v_pk_fma_f32 v[142:143], v[176:177], v[194:195], v[142:143] op_sel_hi:[1,0,1]
	v_pk_fma_f32 v[136:137], v[80:81], v[194:195], v[136:137] op_sel_hi:[1,0,1] neg_lo:[1,0,0] neg_hi:[1,0,0]
	v_pk_fma_f32 v[138:139], v[174:175], v[194:195], v[138:139] op_sel_hi:[1,0,1]
	v_pk_fma_f32 v[132:133], v[92:93], v[194:195], v[132:133] op_sel_hi:[1,0,1] neg_lo:[1,0,0] neg_hi:[1,0,0]
	v_pk_fma_f32 v[128:129], v[88:89], v[194:195], v[128:129] op_sel_hi:[1,0,1] neg_lo:[1,0,0] neg_hi:[1,0,0]
	v_pk_fma_f32 v[134:135], v[94:95], v[194:195], v[134:135] op_sel_hi:[1,0,1]
	v_pk_fma_f32 v[130:131], v[90:91], v[194:195], v[130:131] op_sel_hi:[1,0,1]
	v_cndmask_b32_e32 v194, v179, v191, vcc
	v_pk_add_f32 v[168:169], v[212:213], v[208:209]
	v_pk_add_f32 v[170:171], v[210:211], v[206:207]
	v_pk_fma_f32 v[142:143], v[142:143], v[194:195], v[160:161] op_sel_hi:[1,0,1]
	v_pk_fma_f32 v[140:141], v[140:141], v[194:195], v[162:163] op_sel_hi:[1,0,1]
	v_pk_fma_f32 v[138:139], v[138:139], v[194:195], v[164:165] op_sel_hi:[1,0,1]
	v_pk_fma_f32 v[136:137], v[136:137], v[194:195], v[166:167] op_sel_hi:[1,0,1]
	v_pk_fma_f32 v[196:197], v[130:131], v[194:195], v[168:169] op_sel_hi:[1,0,1]
	v_pk_fma_f32 v[128:129], v[128:129], v[194:195], v[170:171] op_sel_hi:[1,0,1]
	v_max_f32_e32 v130, 0, v140
	v_max_f32_e32 v136, 0, v136
	v_max_f32_e32 v131, 0, v141
	v_max_f32_e32 v137, 0, v137
	v_max_f32_e32 v140, 0, v142
	v_max_f32_e32 v138, 0, v138
	v_max_f32_e32 v141, 0, v143
	v_max_f32_e32 v139, 0, v139
	v_pk_add_f32 v[82:83], v[200:201], v[204:205]
	v_pk_add_f32 v[86:87], v[198:199], v[202:203]
	v_max_f32_e32 v128, 0, v128
	v_max_f32_e32 v129, 0, v129
	v_pk_mul_f32 v[130:131], v[130:131], v[130:131]
	v_pk_mul_f32 v[136:137], v[136:137], v[136:137]
	v_pk_mul_f32 v[140:141], v[140:141], v[140:141]
	v_pk_mul_f32 v[138:139], v[138:139], v[138:139]
	v_pk_fma_f32 v[134:135], v[134:135], v[194:195], v[82:83] op_sel_hi:[1,0,1]
	v_pk_fma_f32 v[132:133], v[132:133], v[194:195], v[86:87] op_sel_hi:[1,0,1]
	v_pk_mul_f32 v[142:143], v[128:129], v[128:129]
	v_cvt_pk_bf16_f32 v128, v130, v131
	v_cvt_pk_bf16_f32 v129, v140, v141
	v_cvt_pk_bf16_f32 v130, v136, v137
	v_cvt_pk_bf16_f32 v131, v138, v139
	v_max_f32_e32 v132, 0, v132
	v_max_f32_e32 v133, 0, v133
	global_store_dwordx4 v[214:215], v[128:131], off
	v_pk_mul_f32 v[132:133], v[132:133], v[132:133]
	s_nop 0
	v_max_f32_e32 v128, 0, v134
	v_max_f32_e32 v130, 0, v196
	v_max_f32_e32 v129, 0, v135
	v_max_f32_e32 v131, 0, v197
	v_pk_mul_f32 v[134:135], v[128:129], v[128:129]
	v_pk_mul_f32 v[136:137], v[130:131], v[130:131]
	v_cvt_pk_bf16_f32 v128, v132, v133
	v_cvt_pk_bf16_f32 v129, v134, v135
	v_cvt_pk_bf16_f32 v130, v142, v143
; __device__ __forceinline__ unsigned pk2(float lo, float hi) { f32x2v v = {lo, hi}; b16x2v b = __builtin_convertvector(v, b16x2v); return __builtin_bit_cast(unsigned, b); }
;     __device__ __forceinline__ bf16_t* O() const { return (bf16_t*)(ws + WS_O); }
;     __device__ __forceinline__ void operator()(const f32x4 (&acc)[2][2][4][2], const Unit& u, int wr, int wc, int fr, int fq) const {
;     ...
;             for (int m = 0; m < 4; ++m) {
;                 const int row = u.pm * 256 + ai * 128 + wr * 64 + m * 16 + fr;
;                 const f32x2v s2 = *(const f32x2v*)(stp + 2 * row); const float mu = s2.x * (1.0f / DM); const float rs = rsqrtf(fmaxf(s2.y * (1.0f / DM) - mu * mu, 0.f) + LN_EPS);
; #pragma unroll
;                 for (int bj = 0; bj < 2; ++bj) {
;                     f32x4 v0 = (acc[ai][bj][m][0] - c1v[bj][0] * mu) * rs + c2v[bj][0], v1 = (acc[ai][bj][m][1] - c1v[bj][1] * mu) * rs + c2v[bj][1];
;                     if (ACT == 1) {
; #pragma unroll
;                         for (int e = 0; e < 4; ++e) { const float a = fmaxf(v0[e], 0.f), c = fmaxf(v1[e], 0.f); v0[e] = a * a; v1[e] = c * c; }
;                     }
;                     v0 = v0 * scale; v1 = v1 * scale;
;                     u32x4 w; w.x = pk2(v0[0], v0[1]); w.y = pk2(v0[2], v0[3]); w.z = pk2(v1[0], v1[1]); w.w = pk2(v1[2], v1[3]);
;                     *(u32x4*)(O + (size_t)row * ldc + colb + 128 * bj) = w;
;                 }
	v_cvt_pk_bf16_f32 v131, v136, v137
	global_store_dwordx4 v[214:215], v[128:131], off offset:256
	v_or_b32_e32 v132, 32, v178
	v_lshlrev_b32_e32 v134, 1, v132
	v_or_b32_e32 v128, 16, v178
	v_lshlrev_b32_e32 v130, 1, v128
	v_ashrrev_i32_e32 v131, 31, v130
	v_lshl_add_u64 v[130:131], v[130:131], 2, s[6:7]
	v_mov_b32_e32 v130, v216
	v_mov_b32_e32 v131, v217
	v_ashrrev_i32_e32 v129, 31, v128
	v_lshlrev_b64 v[128:129], 13, v[128:129]
	v_lshl_add_u64 v[128:129], s[4:5], 0, v[128:129]
	v_ashrrev_i32_e32 v135, 31, v134
	v_lshl_add_u64 v[128:129], v[128:129], 0, v[172:173]
	v_lshl_add_u64 v[134:135], v[134:135], 2, s[6:7]
	s_nop 0
	v_pk_mul_f32 v[130:131], v[130:131], s[22:23] op_sel_hi:[1,0]
	s_nop 0
	v_fma_f32 v133, -v130, v130, v131
	v_max_f32_e32 v133, 0, v133
	v_add_f32_e32 v133, 0x3727c5ac, v133
	v_mul_f32_e32 v136, 0x4b800000, v133
	v_cmp_gt_f32_e32 vcc, s63, v133
	v_pk_fma_f32 v[124:125], v[84:85], v[130:131], v[124:125] op_sel_hi:[1,0,1] neg_lo:[1,0,0] neg_hi:[1,0,0]
	v_pk_fma_f32 v[126:127], v[176:177], v[130:131], v[126:127] op_sel_hi:[1,0,1]
	v_cndmask_b32_e32 v133, v133, v136, vcc
	v_rsq_f32_e32 v133, v133
	v_pk_fma_f32 v[120:121], v[80:81], v[130:131], v[120:121] op_sel_hi:[1,0,1] neg_lo:[1,0,0] neg_hi:[1,0,0]
	v_pk_fma_f32 v[122:123], v[174:175], v[130:131], v[122:123] op_sel_hi:[1,0,1]
	v_pk_fma_f32 v[116:117], v[92:93], v[130:131], v[116:117] op_sel_hi:[1,0,1] neg_lo:[1,0,0] neg_hi:[1,0,0]
	v_pk_fma_f32 v[118:119], v[94:95], v[130:131], v[118:119] op_sel_hi:[1,0,1]
	v_pk_fma_f32 v[112:113], v[88:89], v[130:131], v[112:113] op_sel_hi:[1,0,1] neg_lo:[1,0,0] neg_hi:[1,0,0]
	v_pk_fma_f32 v[114:115], v[90:91], v[130:131], v[114:115] op_sel_hi:[1,0,1]
	v_mul_f32_e32 v130, 0x45800000, v133
	v_cndmask_b32_e32 v130, v133, v130, vcc
	v_pk_fma_f32 v[126:127], v[126:127], v[130:131], v[160:161] op_sel_hi:[1,0,1]
	v_pk_fma_f32 v[124:125], v[124:125], v[130:131], v[162:163] op_sel_hi:[1,0,1]
	v_pk_fma_f32 v[122:123], v[122:123], v[130:131], v[164:165] op_sel_hi:[1,0,1]
	v_pk_fma_f32 v[120:121], v[120:121], v[130:131], v[166:167] op_sel_hi:[1,0,1]
	v_pk_fma_f32 v[118:119], v[118:119], v[130:131], v[82:83] op_sel_hi:[1,0,1]
	v_pk_fma_f32 v[116:117], v[116:117], v[130:131], v[86:87] op_sel_hi:[1,0,1]
	v_pk_fma_f32 v[114:115], v[114:115], v[130:131], v[168:169] op_sel_hi:[1,0,1]
	v_pk_fma_f32 v[112:113], v[112:113], v[130:131], v[170:171] op_sel_hi:[1,0,1]
	v_max_f32_e32 v124, 0, v124
	v_max_f32_e32 v120, 0, v120
	v_max_f32_e32 v125, 0, v125
	v_max_f32_e32 v121, 0, v121
	v_max_f32_e32 v126, 0, v126
	v_max_f32_e32 v122, 0, v122
	v_max_f32_e32 v127, 0, v127
	v_max_f32_e32 v123, 0, v123
	v_max_f32_e32 v116, 0, v116
	v_max_f32_e32 v112, 0, v112
	v_max_f32_e32 v117, 0, v117
	v_max_f32_e32 v113, 0, v113
	v_max_f32_e32 v118, 0, v118
	v_max_f32_e32 v114, 0, v114
	v_max_f32_e32 v119, 0, v119
	v_max_f32_e32 v115, 0, v115
	v_pk_mul_f32 v[124:125], v[124:125], v[124:125]
	v_pk_mul_f32 v[120:121], v[120:121], v[120:121]
	v_pk_mul_f32 v[126:127], v[126:127], v[126:127]
	v_pk_mul_f32 v[122:123], v[122:123], v[122:123]
	v_pk_mul_f32 v[116:117], v[116:117], v[116:117]
	v_pk_mul_f32 v[130:131], v[112:113], v[112:113]
	v_pk_mul_f32 v[118:119], v[118:119], v[118:119]
	v_pk_mul_f32 v[136:137], v[114:115], v[114:115]
	v_cvt_pk_bf16_f32 v112, v124, v125
	v_cvt_pk_bf16_f32 v113, v126, v127
	v_cvt_pk_bf16_f32 v114, v120, v121
	v_cvt_pk_bf16_f32 v115, v122, v123
	v_cvt_pk_bf16_f32 v116, v116, v117
	v_cvt_pk_bf16_f32 v117, v118, v119
	v_cvt_pk_bf16_f32 v118, v130, v131
	v_cvt_pk_bf16_f32 v119, v136, v137
	global_store_dwordx4 v[128:129], v[112:115], off
	global_store_dwordx4 v[128:129], v[116:119], off offset:256
	v_mov_b32_e32 v112, v218
	v_mov_b32_e32 v113, v219
	v_ashrrev_i32_e32 v133, 31, v132
	v_or_b32_e32 v114, 48, v178
	v_lshlrev_b64 v[118:119], 13, v[132:133]
	v_lshlrev_b32_e32 v116, 1, v114
	v_lshl_add_u64 v[118:119], s[4:5], 0, v[118:119]
	v_ashrrev_i32_e32 v117, 31, v116
	v_lshl_add_u64 v[118:119], v[118:119], 0, v[172:173]
	v_lshl_add_u64 v[116:117], v[116:117], 2, s[6:7]
	s_nop 0
	v_pk_mul_f32 v[112:113], v[112:113], s[22:23] op_sel_hi:[1,0]
	s_nop 0
	v_fma_f32 v115, -v112, v112, v113
	v_max_f32_e32 v115, 0, v115
	v_add_f32_e32 v115, 0x3727c5ac, v115
	v_mul_f32_e32 v120, 0x4b800000, v115
	v_cmp_gt_f32_e32 vcc, s63, v115
	v_pk_fma_f32 v[108:109], v[84:85], v[112:113], v[108:109] op_sel_hi:[1,0,1] neg_lo:[1,0,0] neg_hi:[1,0,0]
	v_pk_fma_f32 v[110:111], v[176:177], v[112:113], v[110:111] op_sel_hi:[1,0,1]
	v_cndmask_b32_e32 v115, v115, v120, vcc
	v_rsq_f32_e32 v115, v115
	v_pk_fma_f32 v[104:105], v[80:81], v[112:113], v[104:105] op_sel_hi:[1,0,1] neg_lo:[1,0,0] neg_hi:[1,0,0]
	v_pk_fma_f32 v[106:107], v[174:175], v[112:113], v[106:107] op_sel_hi:[1,0,1]
	v_pk_fma_f32 v[100:101], v[92:93], v[112:113], v[100:101] op_sel_hi:[1,0,1] neg_lo:[1,0,0] neg_hi:[1,0,0]
	v_pk_fma_f32 v[102:103], v[94:95], v[112:113], v[102:103] op_sel_hi:[1,0,1]
	v_pk_fma_f32 v[96:97], v[88:89], v[112:113], v[96:97] op_sel_hi:[1,0,1] neg_lo:[1,0,0] neg_hi:[1,0,0]
	v_pk_fma_f32 v[98:99], v[90:91], v[112:113], v[98:99] op_sel_hi:[1,0,1]
	v_mul_f32_e32 v112, 0x45800000, v115
	v_cndmask_b32_e32 v112, v115, v112, vcc
	v_pk_fma_f32 v[110:111], v[110:111], v[112:113], v[160:161] op_sel_hi:[1,0,1]
	v_pk_fma_f32 v[108:109], v[108:109], v[112:113], v[162:163] op_sel_hi:[1,0,1]
	v_pk_fma_f32 v[106:107], v[106:107], v[112:113], v[164:165] op_sel_hi:[1,0,1]
	v_pk_fma_f32 v[104:105], v[104:105], v[112:113], v[166:167] op_sel_hi:[1,0,1]
	v_pk_fma_f32 v[102:103], v[102:103], v[112:113], v[82:83] op_sel_hi:[1,0,1]
	v_pk_fma_f32 v[100:101], v[100:101], v[112:113], v[86:87] op_sel_hi:[1,0,1]
; __device__ __forceinline__ unsigned pk2(float lo, float hi) { f32x2v v = {lo, hi}; b16x2v b = __builtin_convertvector(v, b16x2v); return __builtin_bit_cast(unsigned, b); }
;     __device__ __forceinline__ bf16_t* O() const { return (bf16_t*)(ws + WS_O); }
;     __device__ __forceinline__ void operator()(const f32x4 (&acc)[2][2][4][2], const Unit& u, int wr, int wc, int fr, int fq) const {
;     ...
;             for (int m = 0; m < 4; ++m) {
;                 const int row = u.pm * 256 + ai * 128 + wr * 64 + m * 16 + fr;
;                 const f32x2v s2 = *(const f32x2v*)(stp + 2 * row); const float mu = s2.x * (1.0f / DM); const float rs = rsqrtf(fmaxf(s2.y * (1.0f / DM) - mu * mu, 0.f) + LN_EPS);
; #pragma unroll
;                 for (int bj = 0; bj < 2; ++bj) {
;                     f32x4 v0 = (acc[ai][bj][m][0] - c1v[bj][0] * mu) * rs + c2v[bj][0], v1 = (acc[ai][bj][m][1] - c1v[bj][1] * mu) * rs + c2v[bj][1];
;                     if (ACT == 1) {
; #pragma unroll
;                         for (int e = 0; e < 4; ++e) { const float a = fmaxf(v0[e], 0.f), c = fmaxf(v1[e], 0.f); v0[e] = a * a; v1[e] = c * c; }
;                     }
;                     v0 = v0 * scale; v1 = v1 * scale;
;                     u32x4 w; w.x = pk2(v0[0], v0[1]); w.y = pk2(v0[2], v0[3]); w.z = pk2(v1[0], v1[1]); w.w = pk2(v1[2], v1[3]);
;                     *(u32x4*)(O + (size_t)row * ldc + colb + 128 * bj) = w;
;                 }
	v_pk_fma_f32 v[98:99], v[98:99], v[112:113], v[168:169] op_sel_hi:[1,0,1]
	v_pk_fma_f32 v[96:97], v[96:97], v[112:113], v[170:171] op_sel_hi:[1,0,1]
	v_max_f32_e32 v108, 0, v108
	v_max_f32_e32 v104, 0, v104
	v_max_f32_e32 v109, 0, v109
	v_max_f32_e32 v105, 0, v105
	v_max_f32_e32 v110, 0, v110
	v_max_f32_e32 v106, 0, v106
	v_max_f32_e32 v111, 0, v111
	v_max_f32_e32 v107, 0, v107
	v_max_f32_e32 v100, 0, v100
	v_max_f32_e32 v96, 0, v96
	v_max_f32_e32 v101, 0, v101
	v_max_f32_e32 v97, 0, v97
	v_max_f32_e32 v102, 0, v102
	v_max_f32_e32 v98, 0, v98
	v_max_f32_e32 v103, 0, v103
	v_max_f32_e32 v99, 0, v99
	v_pk_mul_f32 v[108:109], v[108:109], v[108:109]
	v_pk_mul_f32 v[104:105], v[104:105], v[104:105]
	v_pk_mul_f32 v[110:111], v[110:111], v[110:111]
	v_pk_mul_f32 v[106:107], v[106:107], v[106:107]
	v_pk_mul_f32 v[100:101], v[100:101], v[100:101]
	v_pk_mul_f32 v[112:113], v[96:97], v[96:97]
	v_pk_mul_f32 v[102:103], v[102:103], v[102:103]
	v_pk_mul_f32 v[120:121], v[98:99], v[98:99]
	v_cvt_pk_bf16_f32 v96, v108, v109
	v_cvt_pk_bf16_f32 v97, v110, v111
	v_cvt_pk_bf16_f32 v98, v104, v105
	v_cvt_pk_bf16_f32 v99, v106, v107
	v_cvt_pk_bf16_f32 v100, v100, v101
	v_cvt_pk_bf16_f32 v101, v102, v103
	v_cvt_pk_bf16_f32 v102, v112, v113
	v_cvt_pk_bf16_f32 v103, v120, v121
	global_store_dwordx4 v[118:119], v[96:99], off
	global_store_dwordx4 v[118:119], v[100:103], off offset:256
	v_mov_b32_e32 v96, v220
	v_mov_b32_e32 v97, v221
	v_ashrrev_i32_e32 v115, 31, v114
	v_add_u32_e32 v98, 0x80, v178
	v_lshlrev_b64 v[102:103], 13, v[114:115]
	v_lshlrev_b32_e32 v100, 1, v98
	v_lshl_add_u64 v[102:103], s[4:5], 0, v[102:103]
	v_ashrrev_i32_e32 v101, 31, v100
	v_lshl_add_u64 v[102:103], v[102:103], 0, v[172:173]
	v_lshl_add_u64 v[100:101], v[100:101], 2, s[6:7]
	s_nop 0
	v_pk_mul_f32 v[96:97], v[96:97], s[22:23] op_sel_hi:[1,0]
	s_nop 0
	v_fma_f32 v99, -v96, v96, v97
	v_max_f32_e32 v99, 0, v99
	v_add_f32_e32 v99, 0x3727c5ac, v99
	v_mul_f32_e32 v104, 0x4b800000, v99
	v_cmp_gt_f32_e32 vcc, s63, v99
	v_pk_fma_f32 v[76:77], v[84:85], v[96:97], v[76:77] op_sel_hi:[1,0,1] neg_lo:[1,0,0] neg_hi:[1,0,0]
	v_pk_fma_f32 v[78:79], v[176:177], v[96:97], v[78:79] op_sel_hi:[1,0,1]
	v_cndmask_b32_e32 v99, v99, v104, vcc
	v_rsq_f32_e32 v99, v99
	v_pk_fma_f32 v[72:73], v[80:81], v[96:97], v[72:73] op_sel_hi:[1,0,1] neg_lo:[1,0,0] neg_hi:[1,0,0]
	v_pk_fma_f32 v[74:75], v[174:175], v[96:97], v[74:75] op_sel_hi:[1,0,1]
	v_pk_fma_f32 v[68:69], v[92:93], v[96:97], v[68:69] op_sel_hi:[1,0,1] neg_lo:[1,0,0] neg_hi:[1,0,0]
	v_pk_fma_f32 v[70:71], v[94:95], v[96:97], v[70:71] op_sel_hi:[1,0,1]
	v_pk_fma_f32 v[64:65], v[88:89], v[96:97], v[64:65] op_sel_hi:[1,0,1] neg_lo:[1,0,0] neg_hi:[1,0,0]
	v_pk_fma_f32 v[66:67], v[90:91], v[96:97], v[66:67] op_sel_hi:[1,0,1]
	v_mul_f32_e32 v96, 0x45800000, v99
	v_cndmask_b32_e32 v96, v99, v96, vcc
	v_pk_fma_f32 v[78:79], v[78:79], v[96:97], v[160:161] op_sel_hi:[1,0,1]
	v_pk_fma_f32 v[76:77], v[76:77], v[96:97], v[162:163] op_sel_hi:[1,0,1]
	v_pk_fma_f32 v[74:75], v[74:75], v[96:97], v[164:165] op_sel_hi:[1,0,1]
	v_pk_fma_f32 v[72:73], v[72:73], v[96:97], v[166:167] op_sel_hi:[1,0,1]
	v_pk_fma_f32 v[70:71], v[70:71], v[96:97], v[82:83] op_sel_hi:[1,0,1]
	v_pk_fma_f32 v[68:69], v[68:69], v[96:97], v[86:87] op_sel_hi:[1,0,1]
	v_pk_fma_f32 v[66:67], v[66:67], v[96:97], v[168:169] op_sel_hi:[1,0,1]
	v_pk_fma_f32 v[64:65], v[64:65], v[96:97], v[170:171] op_sel_hi:[1,0,1]
	v_max_f32_e32 v76, 0, v76
	v_max_f32_e32 v72, 0, v72
	v_max_f32_e32 v77, 0, v77
	v_max_f32_e32 v73, 0, v73
	v_max_f32_e32 v78, 0, v78
	v_max_f32_e32 v74, 0, v74
	v_max_f32_e32 v79, 0, v79
	v_max_f32_e32 v75, 0, v75
	v_max_f32_e32 v68, 0, v68
	v_max_f32_e32 v64, 0, v64
	v_max_f32_e32 v69, 0, v69
	v_max_f32_e32 v65, 0, v65
	v_max_f32_e32 v70, 0, v70
	v_max_f32_e32 v66, 0, v66
	v_max_f32_e32 v71, 0, v71
	v_max_f32_e32 v67, 0, v67
	v_pk_mul_f32 v[76:77], v[76:77], v[76:77]
	v_pk_mul_f32 v[72:73], v[72:73], v[72:73]
	v_pk_mul_f32 v[78:79], v[78:79], v[78:79]
	v_pk_mul_f32 v[74:75], v[74:75], v[74:75]
	v_pk_mul_f32 v[68:69], v[68:69], v[68:69]
	v_pk_mul_f32 v[96:97], v[64:65], v[64:65]
	v_pk_mul_f32 v[70:71], v[70:71], v[70:71]
	v_pk_mul_f32 v[104:105], v[66:67], v[66:67]
	v_cvt_pk_bf16_f32 v64, v76, v77
	v_cvt_pk_bf16_f32 v65, v78, v79
	v_cvt_pk_bf16_f32 v66, v72, v73
	v_cvt_pk_bf16_f32 v67, v74, v75
	v_cvt_pk_bf16_f32 v68, v68, v69
	v_cvt_pk_bf16_f32 v69, v70, v71
	v_cvt_pk_bf16_f32 v70, v96, v97
	v_cvt_pk_bf16_f32 v71, v104, v105
	global_store_dwordx4 v[102:103], v[64:67], off
	global_store_dwordx4 v[102:103], v[68:71], off offset:256
	v_mov_b32_e32 v64, v222
	v_mov_b32_e32 v65, v223
	v_ashrrev_i32_e32 v99, 31, v98
	v_add_u32_e32 v66, 0x90, v178
	v_lshlrev_b64 v[70:71], 13, v[98:99]
	v_lshlrev_b32_e32 v68, 1, v66
	v_lshl_add_u64 v[70:71], s[4:5], 0, v[70:71]
	v_ashrrev_i32_e32 v69, 31, v68
	v_lshl_add_u64 v[70:71], v[70:71], 0, v[172:173]
	v_lshl_add_u64 v[68:69], v[68:69], 2, s[6:7]
	s_nop 0
	v_pk_mul_f32 v[64:65], v[64:65], s[22:23] op_sel_hi:[1,0]
	s_nop 0
	v_fma_f32 v67, -v64, v64, v65
	v_max_f32_e32 v67, 0, v67
	v_add_f32_e32 v67, 0x3727c5ac, v67
	v_mul_f32_e32 v72, 0x4b800000, v67
	v_cmp_gt_f32_e32 vcc, s63, v67
	v_pk_fma_f32 v[60:61], v[84:85], v[64:65], v[60:61] op_sel_hi:[1,0,1] neg_lo:[1,0,0] neg_hi:[1,0,0]
	v_pk_fma_f32 v[62:63], v[176:177], v[64:65], v[62:63] op_sel_hi:[1,0,1]
	v_cndmask_b32_e32 v67, v67, v72, vcc
	v_rsq_f32_e32 v67, v67
	v_pk_fma_f32 v[56:57], v[80:81], v[64:65], v[56:57] op_sel_hi:[1,0,1] neg_lo:[1,0,0] neg_hi:[1,0,0]
	v_pk_fma_f32 v[58:59], v[174:175], v[64:65], v[58:59] op_sel_hi:[1,0,1]
	v_pk_fma_f32 v[52:53], v[92:93], v[64:65], v[52:53] op_sel_hi:[1,0,1] neg_lo:[1,0,0] neg_hi:[1,0,0]
; __device__ __forceinline__ unsigned pk2(float lo, float hi) { f32x2v v = {lo, hi}; b16x2v b = __builtin_convertvector(v, b16x2v); return __builtin_bit_cast(unsigned, b); }
;     __device__ __forceinline__ bf16_t* O() const { return (bf16_t*)(ws + WS_O); }
;     __device__ __forceinline__ void operator()(const f32x4 (&acc)[2][2][4][2], const Unit& u, int wr, int wc, int fr, int fq) const {
;     ...
;             for (int m = 0; m < 4; ++m) {
;                 const int row = u.pm * 256 + ai * 128 + wr * 64 + m * 16 + fr;
;                 const f32x2v s2 = *(const f32x2v*)(stp + 2 * row); const float mu = s2.x * (1.0f / DM); const float rs = rsqrtf(fmaxf(s2.y * (1.0f / DM) - mu * mu, 0.f) + LN_EPS);
; #pragma unroll
;                 for (int bj = 0; bj < 2; ++bj) {
;                     f32x4 v0 = (acc[ai][bj][m][0] - c1v[bj][0] * mu) * rs + c2v[bj][0], v1 = (acc[ai][bj][m][1] - c1v[bj][1] * mu) * rs + c2v[bj][1];
;                     if (ACT == 1) {
; #pragma unroll
;                         for (int e = 0; e < 4; ++e) { const float a = fmaxf(v0[e], 0.f), c = fmaxf(v1[e], 0.f); v0[e] = a * a; v1[e] = c * c; }
;                     }
;                     v0 = v0 * scale; v1 = v1 * scale;
;                     u32x4 w; w.x = pk2(v0[0], v0[1]); w.y = pk2(v0[2], v0[3]); w.z = pk2(v1[0], v1[1]); w.w = pk2(v1[2], v1[3]);
;                     *(u32x4*)(O + (size_t)row * ldc + colb + 128 * bj) = w;
;                 }
	v_pk_fma_f32 v[54:55], v[94:95], v[64:65], v[54:55] op_sel_hi:[1,0,1]
	v_pk_fma_f32 v[48:49], v[88:89], v[64:65], v[48:49] op_sel_hi:[1,0,1] neg_lo:[1,0,0] neg_hi:[1,0,0]
	v_pk_fma_f32 v[50:51], v[90:91], v[64:65], v[50:51] op_sel_hi:[1,0,1]
	v_mul_f32_e32 v64, 0x45800000, v67
	v_cndmask_b32_e32 v64, v67, v64, vcc
	v_pk_fma_f32 v[62:63], v[62:63], v[64:65], v[160:161] op_sel_hi:[1,0,1]
	v_pk_fma_f32 v[60:61], v[60:61], v[64:65], v[162:163] op_sel_hi:[1,0,1]
	v_pk_fma_f32 v[58:59], v[58:59], v[64:65], v[164:165] op_sel_hi:[1,0,1]
	v_pk_fma_f32 v[56:57], v[56:57], v[64:65], v[166:167] op_sel_hi:[1,0,1]
	v_pk_fma_f32 v[54:55], v[54:55], v[64:65], v[82:83] op_sel_hi:[1,0,1]
	v_pk_fma_f32 v[52:53], v[52:53], v[64:65], v[86:87] op_sel_hi:[1,0,1]
	v_pk_fma_f32 v[50:51], v[50:51], v[64:65], v[168:169] op_sel_hi:[1,0,1]
	v_pk_fma_f32 v[48:49], v[48:49], v[64:65], v[170:171] op_sel_hi:[1,0,1]
	v_max_f32_e32 v60, 0, v60
	v_max_f32_e32 v56, 0, v56
	v_max_f32_e32 v61, 0, v61
	v_max_f32_e32 v57, 0, v57
	v_max_f32_e32 v62, 0, v62
	v_max_f32_e32 v58, 0, v58
	v_max_f32_e32 v63, 0, v63
	v_max_f32_e32 v59, 0, v59
	v_max_f32_e32 v52, 0, v52
	v_max_f32_e32 v48, 0, v48
	v_max_f32_e32 v53, 0, v53
	v_max_f32_e32 v49, 0, v49
	v_max_f32_e32 v54, 0, v54
	v_max_f32_e32 v50, 0, v50
	v_max_f32_e32 v55, 0, v55
	v_max_f32_e32 v51, 0, v51
	v_pk_mul_f32 v[60:61], v[60:61], v[60:61]
	v_pk_mul_f32 v[56:57], v[56:57], v[56:57]
	v_pk_mul_f32 v[62:63], v[62:63], v[62:63]
	v_pk_mul_f32 v[58:59], v[58:59], v[58:59]
	v_pk_mul_f32 v[52:53], v[52:53], v[52:53]
	v_pk_mul_f32 v[64:65], v[48:49], v[48:49]
	v_pk_mul_f32 v[54:55], v[54:55], v[54:55]
	v_pk_mul_f32 v[72:73], v[50:51], v[50:51]
	v_cvt_pk_bf16_f32 v48, v60, v61
	v_cvt_pk_bf16_f32 v49, v62, v63
	v_cvt_pk_bf16_f32 v50, v56, v57
	v_cvt_pk_bf16_f32 v51, v58, v59
	v_cvt_pk_bf16_f32 v52, v52, v53
	v_cvt_pk_bf16_f32 v53, v54, v55
	v_cvt_pk_bf16_f32 v54, v64, v65
	v_cvt_pk_bf16_f32 v55, v72, v73
	global_store_dwordx4 v[70:71], v[48:51], off
	global_store_dwordx4 v[70:71], v[52:55], off offset:256
	v_mov_b32_e32 v48, v224
	v_mov_b32_e32 v49, v225
	v_ashrrev_i32_e32 v67, 31, v66
	v_add_u32_e32 v50, 0xa0, v178
	v_lshlrev_b64 v[54:55], 13, v[66:67]
	v_lshlrev_b32_e32 v52, 1, v50
	v_lshl_add_u64 v[54:55], s[4:5], 0, v[54:55]
	v_ashrrev_i32_e32 v53, 31, v52
	v_lshl_add_u64 v[54:55], v[54:55], 0, v[172:173]
	v_lshl_add_u64 v[52:53], v[52:53], 2, s[6:7]
	s_nop 0
	v_pk_mul_f32 v[48:49], v[48:49], s[22:23] op_sel_hi:[1,0]
	s_nop 0
	v_fma_f32 v51, -v48, v48, v49
	v_max_f32_e32 v51, 0, v51
	v_add_f32_e32 v51, 0x3727c5ac, v51
	v_mul_f32_e32 v56, 0x4b800000, v51
	v_cmp_gt_f32_e32 vcc, s63, v51
	v_pk_fma_f32 v[44:45], v[84:85], v[48:49], v[44:45] op_sel_hi:[1,0,1] neg_lo:[1,0,0] neg_hi:[1,0,0]
	v_pk_fma_f32 v[46:47], v[176:177], v[48:49], v[46:47] op_sel_hi:[1,0,1]
	v_cndmask_b32_e32 v51, v51, v56, vcc
	v_rsq_f32_e32 v51, v51
	v_pk_fma_f32 v[40:41], v[80:81], v[48:49], v[40:41] op_sel_hi:[1,0,1] neg_lo:[1,0,0] neg_hi:[1,0,0]
	v_pk_fma_f32 v[42:43], v[174:175], v[48:49], v[42:43] op_sel_hi:[1,0,1]
	v_pk_fma_f32 v[36:37], v[92:93], v[48:49], v[36:37] op_sel_hi:[1,0,1] neg_lo:[1,0,0] neg_hi:[1,0,0]
	v_pk_fma_f32 v[38:39], v[94:95], v[48:49], v[38:39] op_sel_hi:[1,0,1]
	v_pk_fma_f32 v[32:33], v[88:89], v[48:49], v[32:33] op_sel_hi:[1,0,1] neg_lo:[1,0,0] neg_hi:[1,0,0]
	v_pk_fma_f32 v[34:35], v[90:91], v[48:49], v[34:35] op_sel_hi:[1,0,1]
	v_mul_f32_e32 v48, 0x45800000, v51
	v_cndmask_b32_e32 v48, v51, v48, vcc
	v_pk_fma_f32 v[46:47], v[46:47], v[48:49], v[160:161] op_sel_hi:[1,0,1]
	v_pk_fma_f32 v[44:45], v[44:45], v[48:49], v[162:163] op_sel_hi:[1,0,1]
	v_pk_fma_f32 v[42:43], v[42:43], v[48:49], v[164:165] op_sel_hi:[1,0,1]
	v_pk_fma_f32 v[40:41], v[40:41], v[48:49], v[166:167] op_sel_hi:[1,0,1]
	v_pk_fma_f32 v[38:39], v[38:39], v[48:49], v[82:83] op_sel_hi:[1,0,1]
	v_pk_fma_f32 v[36:37], v[36:37], v[48:49], v[86:87] op_sel_hi:[1,0,1]
	v_pk_fma_f32 v[34:35], v[34:35], v[48:49], v[168:169] op_sel_hi:[1,0,1]
	v_pk_fma_f32 v[32:33], v[32:33], v[48:49], v[170:171] op_sel_hi:[1,0,1]
	v_max_f32_e32 v44, 0, v44
	v_max_f32_e32 v40, 0, v40
	v_max_f32_e32 v45, 0, v45
	v_max_f32_e32 v41, 0, v41
	v_max_f32_e32 v46, 0, v46
	v_max_f32_e32 v42, 0, v42
	v_max_f32_e32 v47, 0, v47
	v_max_f32_e32 v43, 0, v43
	v_max_f32_e32 v36, 0, v36
	v_max_f32_e32 v32, 0, v32
	v_max_f32_e32 v37, 0, v37
	v_max_f32_e32 v33, 0, v33
	v_max_f32_e32 v38, 0, v38
	v_max_f32_e32 v34, 0, v34
	v_max_f32_e32 v39, 0, v39
	v_max_f32_e32 v35, 0, v35
	v_pk_mul_f32 v[44:45], v[44:45], v[44:45]
	v_pk_mul_f32 v[40:41], v[40:41], v[40:41]
	v_pk_mul_f32 v[46:47], v[46:47], v[46:47]
	v_pk_mul_f32 v[42:43], v[42:43], v[42:43]
	v_pk_mul_f32 v[36:37], v[36:37], v[36:37]
	v_pk_mul_f32 v[48:49], v[32:33], v[32:33]
	v_pk_mul_f32 v[38:39], v[38:39], v[38:39]
	v_pk_mul_f32 v[56:57], v[34:35], v[34:35]
	v_cvt_pk_bf16_f32 v32, v44, v45
	v_cvt_pk_bf16_f32 v33, v46, v47
	v_cvt_pk_bf16_f32 v34, v40, v41
	v_cvt_pk_bf16_f32 v35, v42, v43
	v_cvt_pk_bf16_f32 v36, v36, v37
	v_cvt_pk_bf16_f32 v37, v38, v39
	v_cvt_pk_bf16_f32 v38, v48, v49
	v_cvt_pk_bf16_f32 v39, v56, v57
	global_store_dwordx4 v[54:55], v[32:35], off
	global_store_dwordx4 v[54:55], v[36:39], off offset:256
	v_mov_b32_e32 v32, v226
	v_mov_b32_e32 v33, v227
	v_ashrrev_i32_e32 v51, 31, v50
	v_add_u32_e32 v34, 0xb0, v178
	v_lshlrev_b64 v[38:39], 13, v[50:51]
	v_lshlrev_b32_e32 v36, 1, v34
	v_lshl_add_u64 v[38:39], s[4:5], 0, v[38:39]
	v_ashrrev_i32_e32 v37, 31, v36
	v_lshl_add_u64 v[38:39], v[38:39], 0, v[172:173]
	v_lshl_add_u64 v[36:37], v[36:37], 2, s[6:7]
	s_nop 0
	v_pk_mul_f32 v[32:33], v[32:33], s[22:23] op_sel_hi:[1,0]
	s_nop 0
	v_fma_f32 v35, -v32, v32, v33
; __device__ __forceinline__ unsigned pk2(float lo, float hi) { f32x2v v = {lo, hi}; b16x2v b = __builtin_convertvector(v, b16x2v); return __builtin_bit_cast(unsigned, b); }
;     __device__ __forceinline__ bf16_t* O() const { return (bf16_t*)(ws + WS_O); }
;     __device__ __forceinline__ void operator()(const f32x4 (&acc)[2][2][4][2], const Unit& u, int wr, int wc, int fr, int fq) const {
;     ...
;             for (int m = 0; m < 4; ++m) {
;                 const int row = u.pm * 256 + ai * 128 + wr * 64 + m * 16 + fr;
;                 const f32x2v s2 = *(const f32x2v*)(stp + 2 * row); const float mu = s2.x * (1.0f / DM); const float rs = rsqrtf(fmaxf(s2.y * (1.0f / DM) - mu * mu, 0.f) + LN_EPS);
; #pragma unroll
;                 for (int bj = 0; bj < 2; ++bj) {
;                     f32x4 v0 = (acc[ai][bj][m][0] - c1v[bj][0] * mu) * rs + c2v[bj][0], v1 = (acc[ai][bj][m][1] - c1v[bj][1] * mu) * rs + c2v[bj][1];
;                     if (ACT == 1) {
; #pragma unroll
;                         for (int e = 0; e < 4; ++e) { const float a = fmaxf(v0[e], 0.f), c = fmaxf(v1[e], 0.f); v0[e] = a * a; v1[e] = c * c; }
;                     }
;                     v0 = v0 * scale; v1 = v1 * scale;
;                     u32x4 w; w.x = pk2(v0[0], v0[1]); w.y = pk2(v0[2], v0[3]); w.z = pk2(v1[0], v1[1]); w.w = pk2(v1[2], v1[3]);
;                     *(u32x4*)(O + (size_t)row * ldc + colb + 128 * bj) = w;
;                 }
;             }
;     }
	v_max_f32_e32 v35, 0, v35
	v_add_f32_e32 v35, 0x3727c5ac, v35
	v_mul_f32_e32 v40, 0x4b800000, v35
	v_cmp_gt_f32_e32 vcc, s63, v35
	v_pk_fma_f32 v[28:29], v[84:85], v[32:33], v[28:29] op_sel_hi:[1,0,1] neg_lo:[1,0,0] neg_hi:[1,0,0]
	v_pk_fma_f32 v[30:31], v[176:177], v[32:33], v[30:31] op_sel_hi:[1,0,1]
	v_cndmask_b32_e32 v35, v35, v40, vcc
	v_rsq_f32_e32 v35, v35
	v_pk_fma_f32 v[24:25], v[80:81], v[32:33], v[24:25] op_sel_hi:[1,0,1] neg_lo:[1,0,0] neg_hi:[1,0,0]
	v_pk_fma_f32 v[26:27], v[174:175], v[32:33], v[26:27] op_sel_hi:[1,0,1]
	v_pk_fma_f32 v[20:21], v[92:93], v[32:33], v[20:21] op_sel_hi:[1,0,1] neg_lo:[1,0,0] neg_hi:[1,0,0]
	v_pk_fma_f32 v[22:23], v[94:95], v[32:33], v[22:23] op_sel_hi:[1,0,1]
	v_pk_fma_f32 v[16:17], v[88:89], v[32:33], v[16:17] op_sel_hi:[1,0,1] neg_lo:[1,0,0] neg_hi:[1,0,0]
	v_pk_fma_f32 v[18:19], v[90:91], v[32:33], v[18:19] op_sel_hi:[1,0,1]
	v_mul_f32_e32 v32, 0x45800000, v35
	v_cndmask_b32_e32 v32, v35, v32, vcc
	v_pk_fma_f32 v[30:31], v[30:31], v[32:33], v[160:161] op_sel_hi:[1,0,1]
	v_pk_fma_f32 v[28:29], v[28:29], v[32:33], v[162:163] op_sel_hi:[1,0,1]
	v_pk_fma_f32 v[26:27], v[26:27], v[32:33], v[164:165] op_sel_hi:[1,0,1]
	v_pk_fma_f32 v[24:25], v[24:25], v[32:33], v[166:167] op_sel_hi:[1,0,1]
	v_pk_fma_f32 v[22:23], v[22:23], v[32:33], v[82:83] op_sel_hi:[1,0,1]
	v_pk_fma_f32 v[20:21], v[20:21], v[32:33], v[86:87] op_sel_hi:[1,0,1]
	v_pk_fma_f32 v[18:19], v[18:19], v[32:33], v[168:169] op_sel_hi:[1,0,1]
	v_pk_fma_f32 v[16:17], v[16:17], v[32:33], v[170:171] op_sel_hi:[1,0,1]
	v_max_f32_e32 v28, 0, v28
	v_max_f32_e32 v24, 0, v24
	v_max_f32_e32 v29, 0, v29
	v_max_f32_e32 v25, 0, v25
	v_max_f32_e32 v30, 0, v30
	v_max_f32_e32 v26, 0, v26
	v_max_f32_e32 v31, 0, v31
	v_max_f32_e32 v27, 0, v27
	v_max_f32_e32 v20, 0, v20
	v_max_f32_e32 v16, 0, v16
	v_max_f32_e32 v21, 0, v21
	v_max_f32_e32 v17, 0, v17
	v_max_f32_e32 v22, 0, v22
	v_max_f32_e32 v18, 0, v18
	v_max_f32_e32 v23, 0, v23
	v_max_f32_e32 v19, 0, v19
	v_pk_mul_f32 v[28:29], v[28:29], v[28:29]
	v_pk_mul_f32 v[24:25], v[24:25], v[24:25]
	v_pk_mul_f32 v[30:31], v[30:31], v[30:31]
	v_pk_mul_f32 v[26:27], v[26:27], v[26:27]
	v_pk_mul_f32 v[20:21], v[20:21], v[20:21]
	v_pk_mul_f32 v[32:33], v[16:17], v[16:17]
	v_pk_mul_f32 v[22:23], v[22:23], v[22:23]
	v_pk_mul_f32 v[40:41], v[18:19], v[18:19]
	v_cvt_pk_bf16_f32 v16, v28, v29
	v_cvt_pk_bf16_f32 v17, v30, v31
	v_cvt_pk_bf16_f32 v18, v24, v25
	v_cvt_pk_bf16_f32 v19, v26, v27
	v_cvt_pk_bf16_f32 v20, v20, v21
	v_cvt_pk_bf16_f32 v21, v22, v23
	v_cvt_pk_bf16_f32 v22, v32, v33
	v_cvt_pk_bf16_f32 v23, v40, v41
	global_store_dwordx4 v[38:39], v[16:19], off
	global_store_dwordx4 v[38:39], v[20:23], off offset:256
	v_mov_b32_e32 v16, v228
	v_mov_b32_e32 v17, v229
	v_ashrrev_i32_e32 v35, 31, v34
	v_lshlrev_b64 v[18:19], 13, v[34:35]
	v_lshl_add_u64 v[18:19], s[4:5], 0, v[18:19]
	s_andn2_b64 vcc, exec, s[2:3]
	v_lshl_add_u64 v[18:19], v[18:19], 0, v[172:173]
	s_nop 0
	v_pk_mul_f32 v[16:17], v[16:17], s[22:23] op_sel_hi:[1,0]
	s_nop 0
	v_fma_f32 v20, -v16, v16, v17
	v_max_f32_e32 v20, 0, v20
	v_add_f32_e32 v20, 0x3727c5ac, v20
	v_mul_f32_e32 v21, 0x4b800000, v20
	v_cmp_gt_f32_e64 s[0:1], s63, v20
	v_pk_fma_f32 v[12:13], v[84:85], v[16:17], v[12:13] op_sel_hi:[1,0,1] neg_lo:[1,0,0] neg_hi:[1,0,0]
	v_pk_fma_f32 v[14:15], v[176:177], v[16:17], v[14:15] op_sel_hi:[1,0,1]
	v_cndmask_b32_e64 v20, v20, v21, s[0:1]
	v_rsq_f32_e32 v20, v20
	v_pk_fma_f32 v[8:9], v[80:81], v[16:17], v[8:9] op_sel_hi:[1,0,1] neg_lo:[1,0,0] neg_hi:[1,0,0]
	v_pk_fma_f32 v[10:11], v[174:175], v[16:17], v[10:11] op_sel_hi:[1,0,1]
	v_pk_fma_f32 v[4:5], v[92:93], v[16:17], v[4:5] op_sel_hi:[1,0,1] neg_lo:[1,0,0] neg_hi:[1,0,0]
	v_pk_fma_f32 v[6:7], v[94:95], v[16:17], v[6:7] op_sel_hi:[1,0,1]
	v_pk_fma_f32 v[0:1], v[88:89], v[16:17], v[0:1] op_sel_hi:[1,0,1] neg_lo:[1,0,0] neg_hi:[1,0,0]
	v_pk_fma_f32 v[2:3], v[90:91], v[16:17], v[2:3] op_sel_hi:[1,0,1]
	v_mul_f32_e32 v16, 0x45800000, v20
	v_cndmask_b32_e64 v16, v20, v16, s[0:1]
	v_pk_fma_f32 v[14:15], v[14:15], v[16:17], v[160:161] op_sel_hi:[1,0,1]
	v_pk_fma_f32 v[12:13], v[12:13], v[16:17], v[162:163] op_sel_hi:[1,0,1]
	v_pk_fma_f32 v[10:11], v[10:11], v[16:17], v[164:165] op_sel_hi:[1,0,1]
	v_pk_fma_f32 v[8:9], v[8:9], v[16:17], v[166:167] op_sel_hi:[1,0,1]
	v_pk_fma_f32 v[6:7], v[6:7], v[16:17], v[82:83] op_sel_hi:[1,0,1]
	v_pk_fma_f32 v[4:5], v[4:5], v[16:17], v[86:87] op_sel_hi:[1,0,1]
	v_pk_fma_f32 v[2:3], v[2:3], v[16:17], v[168:169] op_sel_hi:[1,0,1]
	v_pk_fma_f32 v[0:1], v[0:1], v[16:17], v[170:171] op_sel_hi:[1,0,1]
	v_max_f32_e32 v12, 0, v12
	v_max_f32_e32 v8, 0, v8
	v_max_f32_e32 v13, 0, v13
	v_max_f32_e32 v9, 0, v9
	v_max_f32_e32 v14, 0, v14
	v_max_f32_e32 v10, 0, v10
	v_max_f32_e32 v15, 0, v15
	v_max_f32_e32 v11, 0, v11
	v_max_f32_e32 v4, 0, v4
	v_max_f32_e32 v0, 0, v0
	v_max_f32_e32 v5, 0, v5
	v_max_f32_e32 v1, 0, v1
	v_max_f32_e32 v6, 0, v6
	v_max_f32_e32 v2, 0, v2
	v_max_f32_e32 v7, 0, v7
	v_max_f32_e32 v3, 0, v3
	v_pk_mul_f32 v[12:13], v[12:13], v[12:13]
	v_pk_mul_f32 v[8:9], v[8:9], v[8:9]
	v_pk_mul_f32 v[14:15], v[14:15], v[14:15]
	v_pk_mul_f32 v[10:11], v[10:11], v[10:11]
	v_pk_mul_f32 v[4:5], v[4:5], v[4:5]
	v_pk_mul_f32 v[16:17], v[0:1], v[0:1]
	v_pk_mul_f32 v[6:7], v[6:7], v[6:7]
	v_pk_mul_f32 v[20:21], v[2:3], v[2:3]
	v_cvt_pk_bf16_f32 v0, v12, v13
	v_cvt_pk_bf16_f32 v1, v14, v15
	v_cvt_pk_bf16_f32 v2, v8, v9
	v_cvt_pk_bf16_f32 v3, v10, v11
	s_mov_b64 s[0:1], -1
	v_cvt_pk_bf16_f32 v4, v4, v5
	v_cvt_pk_bf16_f32 v5, v6, v7
	v_cvt_pk_bf16_f32 v6, v16, v17
	v_cvt_pk_bf16_f32 v7, v20, v21
	global_store_dwordx4 v[18:19], v[0:3], off
	global_store_dwordx4 v[18:19], v[4:7], off offset:256
	s_cbranch_vccnz .LBB0_1112
	s_andn2_b64 vcc, exec, s[16:17]
	s_cbranch_vccnz .LBB0_1111
	s_barrier
	s_branch .LBB0_1111
